# attention loop: 32-bit tile offsets over zeroed high halves, compares against s61 (6 fewer scalar instructions per step pair)
# baseline (speedup 1.0000x reference)
.LBB0_449:
	s_ashr_i32 s79, s78, 31
	s_lshl_b64 s[2:3], s[78:79], 13
	v_or_b32_e32 v34, s34, v215
	v_or_b32_e32 v196, s2, v34
	v_mov_b32_e32 v197, s3
	v_lshlrev_b64 v[4:5], 12, v[196:197]
	s_lshl_b32 s57, s10, 7
	s_lshl_b32 s10, s10, 8
	v_lshl_add_u64 v[4:5], s[22:23], 0, v[4:5]
	v_lshl_add_u64 v[4:5], v[4:5], 0, s[10:11]
	s_mov_b32 s39, s11
	v_lshl_add_u64 v[4:5], v[4:5], 0, s[38:39]
	v_mov_b32_e32 v183, v153
	v_lshl_add_u64 v[4:5], v[4:5], 0, v[182:183]
	global_load_dwordx4 v[130:133], v[4:5], off
	global_load_dwordx4 v[134:137], v[4:5], off offset:32
	global_load_dwordx4 v[138:141], v[4:5], off offset:64
	global_load_dwordx4 v[142:145], v[4:5], off offset:96
	v_lshl_add_u64 v[2:3], s[2:3], 0, v[150:151]
	v_lshlrev_b64 v[2:3], 12, v[2:3]
	v_lshl_add_u64 v[2:3], s[22:23], 0, v[2:3]
	v_lshl_add_u64 v[2:3], v[2:3], 0, s[10:11]
	v_lshl_add_u64 v[202:203], v[2:3], 0, v[152:153]
	v_add_u32_e32 v0, s57, v216
	v_mov_b64_e32 v[2:3], s[28:29]
	v_mad_u64_u32 v[6:7], s[2:3], v0, s42, v[2:3]
	v_add_u32_e32 v0, s57, v217
	s_lshl_b64 s[2:3], s[78:79], 14
	v_mad_u64_u32 v[2:3], s[60:61], v0, s42, v[2:3]
	v_lshl_add_u64 v[6:7], v[6:7], 0, s[2:3]
	v_lshl_add_u64 v[2:3], v[2:3], 0, s[2:3]
	s_lshl_b32 s2, s48, 1
	v_mov_b32_e32 v181, v153
	s_sub_i32 s39, s2, s33
	s_lshl_b32 s2, s34, 12
	s_mov_b32 s3, s11
	v_mov_b32_e32 v179, v153
	v_lshl_add_u64 v[206:207], v[2:3], 0, v[180:181]
	v_lshl_add_u64 v[2:3], v[202:203], 0, s[2:3]
	s_mov_b32 m0, s7
	v_lshl_add_u64 v[204:205], v[6:7], 0, v[178:179]
	v_lshl_add_u64 v[6:7], v[2:3], 0, s[30:31]
	s_add_i32 s3, s7, 0x2000
	s_or_b32 s2, s34, 64
	global_load_lds_dwordx4 v[6:7], off
	v_lshl_add_u64 v[2:3], v[2:3], 0, s[36:37]
	s_mov_b32 m0, s3
	s_lshl_b32 s60, s2, 12
	s_mov_b32 s61, s11
	global_load_lds_dwordx4 v[2:3], off
	v_lshl_add_u64 v[2:3], v[202:203], 0, s[60:61]
	s_lshl_b32 s60, s33, 6
	s_add_i32 s5, s60, 0x80
	s_cmp_gt_i32 s39, 0
	s_cselect_b32 s62, s60, s5
	v_lshl_add_u64 v[6:7], v[2:3], 0, s[30:31]
	s_mov_b32 m0, s43
	s_ashr_i32 s63, s62, 31
	global_load_lds_dwordx4 v[6:7], off
	v_lshl_add_u64 v[2:3], v[2:3], 0, s[36:37]
	s_mov_b32 m0, s49
	s_lshl_b64 s[62:63], s[62:63], 12
	global_load_lds_dwordx4 v[2:3], off
	v_lshl_add_u64 v[2:3], v[202:203], 0, s[62:63]
	v_lshl_add_u64 v[6:7], v[2:3], 0, s[30:31]
	s_mov_b32 m0, s50
	v_lshl_add_u64 v[2:3], v[2:3], 0, s[36:37]
	global_load_lds_dwordx4 v[6:7], off
	s_mov_b32 m0, s51
	s_lshl_b32 s62, s34, 1
	s_mov_b32 s63, s11
	global_load_lds_dwordx4 v[2:3], off
	v_lshl_add_u64 v[44:45], v[204:205], 0, s[62:63]
	s_mov_b32 m0, s52
	v_lshl_add_u64 v[46:47], v[206:207], 0, s[62:63]
	global_load_lds_dwordx4 v[44:45], off
	s_mov_b32 m0, s53
	v_add_u32_e32 v35, v218, v149
	global_load_lds_dwordx4 v[46:47], off
	s_waitcnt vmcnt(6) lgkmcnt(0)
	s_barrier
	ds_read_b128 v[18:21], v35
	ds_read_b128 v[36:39], v35 offset:4096
	v_and_b32_e32 v155, 0x7fffffff, v1
	v_mov_b32_e32 v0, v201
	v_pk_mul_f32 v[16:17], v[170:171], v[0:1] op_sel_hi:[1,0] neg_lo:[0,1] neg_hi:[0,1]
	v_pk_mul_f32 v[14:15], v[168:169], v[0:1] op_sel_hi:[1,0] neg_lo:[0,1] neg_hi:[0,1]
	v_pk_mul_f32 v[12:13], v[166:167], v[0:1] op_sel_hi:[1,0] neg_lo:[0,1] neg_hi:[0,1]
	v_pk_mul_f32 v[10:11], v[164:165], v[0:1] op_sel_hi:[1,0] neg_lo:[0,1] neg_hi:[0,1]
	v_pk_mul_f32 v[8:9], v[162:163], v[0:1] op_sel_hi:[1,0] neg_lo:[0,1] neg_hi:[0,1]
	v_pk_mul_f32 v[6:7], v[158:159], v[0:1] op_sel_hi:[1,0] neg_lo:[0,1] neg_hi:[0,1]
	v_pk_mul_f32 v[4:5], v[156:157], v[0:1] op_sel_hi:[1,0] neg_lo:[0,1] neg_hi:[0,1]
	v_pk_mul_f32 v[2:3], v[154:155], v[0:1] op_sel_hi:[1,0] neg_lo:[0,1] neg_hi:[0,1]
	v_pk_mul_f32 v[32:33], v[192:193], v[0:1] op_sel_hi:[1,0] neg_lo:[0,1] neg_hi:[0,1]
	v_pk_mul_f32 v[30:31], v[190:191], v[0:1] op_sel_hi:[1,0] neg_lo:[0,1] neg_hi:[0,1]
	s_waitcnt vmcnt(0) lgkmcnt(0)
	v_mfma_f32_32x32x16_bf16 v[2:17], v[18:21], v[130:133], v[2:17]
	v_mul_f32_e64 v28, v188, -v0
	v_mul_f32_e64 v29, v189, -v0
	v_mul_f32_e64 v26, v186, -v0
	v_mul_f32_e64 v27, v187, -v0
	v_mul_f32_e64 v24, v184, -v0
	v_mul_f32_e64 v25, v185, -v0
	v_pk_mul_f32 v[22:23], v[176:177], v[0:1] op_sel_hi:[1,0] neg_lo:[0,1] neg_hi:[0,1]
	v_pk_mul_f32 v[20:21], v[174:175], v[0:1] op_sel_hi:[1,0] neg_lo:[0,1] neg_hi:[0,1]
	v_pk_mul_f32 v[18:19], v[172:173], v[0:1] op_sel_hi:[1,0] neg_lo:[0,1] neg_hi:[0,1]
	v_add_u32_e32 v48, v218, v208
	v_add_u32_e32 v49, v218, v209
	v_mfma_f32_32x32x16_bf16 v[18:33], v[36:39], v[130:133], v[18:33]
	ds_read_b128 v[36:39], v48
	ds_read_b128 v[40:43], v48 offset:4096
	v_add_u32_e32 v50, v218, v226
	s_sub_i32 s48, s4, s33
	s_cmp_gt_i32 s39, 1
	s_cselect_b32 s4, 1, 3
	s_add_i32 s4, s4, s33
	s_lshl_b32 s4, s4, 6
	s_waitcnt lgkmcnt(1)
	v_mfma_f32_32x32x16_bf16 v[2:17], v[36:39], v[134:137], v[2:17]
	s_ashr_i32 s5, s4, 31
	s_lshl_b64 s[4:5], s[4:5], 12
	s_mov_b32 m0, s7
	s_mov_b32 s10, 0
	s_waitcnt lgkmcnt(0)
	v_mfma_f32_32x32x16_bf16 v[18:33], v[40:43], v[134:137], v[18:33]
	ds_read_b128 v[36:39], v49
	ds_read_b128 v[40:43], v49 offset:4096
	s_waitcnt lgkmcnt(1)
	v_mfma_f32_32x32x16_bf16 v[2:17], v[36:39], v[138:141], v[2:17]
	ds_read_b128 v[36:39], v50
	s_waitcnt lgkmcnt(1)
	v_mfma_f32_32x32x16_bf16 v[18:33], v[40:43], v[138:141], v[18:33]
	ds_read_b128 v[40:43], v50 offset:4096
	s_waitcnt vmcnt(4) lgkmcnt(0)
	s_barrier
	s_waitcnt lgkmcnt(1)
	v_mfma_f32_32x32x16_bf16 v[2:17], v[36:39], v[142:145], v[2:17]
	v_lshl_add_u64 v[36:37], v[202:203], 0, s[4:5]
	v_lshl_add_u64 v[38:39], v[36:37], 0, s[30:31]
	global_load_lds_dwordx4 v[38:39], off
	v_lshl_add_u64 v[36:37], v[36:37], 0, s[36:37]
	s_mov_b32 m0, s3
	v_or_b32_e32 v38, s2, v148
	global_load_lds_dwordx4 v[36:37], off
	v_lshl_add_u64 v[36:37], v[44:45], 0, s[40:41]
	s_mov_b32 m0, s54
	s_waitcnt lgkmcnt(0)
	v_mfma_f32_32x32x16_bf16 v[18:33], v[40:43], v[142:145], v[18:33]
	global_load_lds_dwordx4 v[36:37], off
	v_lshl_add_u64 v[36:37], v[46:47], 0, s[40:41]
	s_mov_b32 m0, s55
	s_nop 0
	global_load_lds_dwordx4 v[36:37], off
	v_max3_f32 v36, v2, v3, v18
	v_max3_f32 v37, v4, v5, v19
	s_nop 15
	s_nop 15
	s_nop 15
	s_nop 0
	v_max3_f32 v36, v36, v20, v21
	v_max3_f32 v37, v37, v8, v9
	s_nop 0
	v_max3_f32 v36, v36, v6, v7
	v_max3_f32 v37, v37, v24, v25
	s_nop 0
	v_max3_f32 v36, v36, v22, v23
	v_max3_f32 v37, v37, v12, v13
	s_nop 0
	v_max3_f32 v36, v36, v10, v11
	v_max3_f32 v37, v37, v28, v29
	s_nop 0
	v_max3_f32 v36, v36, v26, v27
	v_max3_f32 v37, v37, v16, v17
	s_nop 0
	v_max3_f32 v36, v36, v14, v15
	v_max3_f32 v37, v37, v32, v33
	s_nop 0
	v_max3_f32 v36, v36, v30, v31
	s_nop 0
	v_max_f32_e32 v36, v36, v37
	s_nop 0
	v_mov_b32_e32 v37, v36
	s_nop 1
	v_permlane32_swap_b32 v36, v37
	s_nop 1
	s_nop 0
	v_max_f32_e32 v37, v37, v37
	v_max_f32_e32 v36, v36, v36
	v_max_f32_e32 v37, v36, v37
	v_sub_f32_e32 v2, v2, v37
	v_sub_f32_e32 v18, v18, v37
	v_sub_f32_e32 v3, v3, v37
	v_sub_f32_e32 v19, v19, v37
	v_sub_f32_e32 v4, v4, v37
	v_sub_f32_e32 v20, v20, v37
	v_sub_f32_e32 v5, v5, v37
	v_sub_f32_e32 v21, v21, v37
	v_sub_f32_e32 v6, v6, v37
	v_sub_f32_e32 v22, v22, v37
	v_sub_f32_e32 v7, v7, v37
	v_sub_f32_e32 v23, v23, v37
	v_sub_f32_e32 v8, v8, v37
	v_sub_f32_e32 v24, v24, v37
	v_sub_f32_e32 v9, v9, v37
	v_sub_f32_e32 v25, v25, v37
	v_sub_f32_e32 v10, v10, v37
	v_sub_f32_e32 v26, v26, v37
	v_sub_f32_e32 v11, v11, v37
	v_sub_f32_e32 v27, v27, v37
	v_sub_f32_e32 v12, v12, v37
	v_sub_f32_e32 v28, v28, v37
	v_sub_f32_e32 v13, v13, v37
	v_sub_f32_e32 v29, v29, v37
	v_sub_f32_e32 v14, v14, v37
	v_sub_f32_e32 v30, v30, v37
	v_sub_f32_e32 v15, v15, v37
	v_sub_f32_e32 v31, v31, v37
	v_sub_f32_e32 v16, v16, v37
	v_sub_f32_e32 v32, v32, v37
	v_sub_f32_e32 v17, v17, v37
	v_sub_f32_e32 v33, v33, v37
	v_exp_f32_e32 v52, v2
	v_exp_f32_e32 v53, v18
	v_exp_f32_e32 v54, v3
	v_exp_f32_e32 v55, v19
	v_exp_f32_e32 v56, v4
	v_exp_f32_e32 v57, v20
	v_exp_f32_e32 v58, v5
	v_exp_f32_e32 v59, v21
	v_exp_f32_e32 v60, v6
	v_exp_f32_e32 v61, v22
	v_exp_f32_e32 v62, v7
	v_exp_f32_e32 v63, v23
	v_exp_f32_e32 v64, v8
	v_exp_f32_e32 v65, v24
	v_exp_f32_e32 v101, v9
	v_exp_f32_e32 v102, v25
	v_exp_f32_e32 v103, v10
	v_exp_f32_e32 v104, v26
	v_exp_f32_e32 v114, v27
	v_exp_f32_e32 v105, v11
	v_exp_f32_e32 v107, v12
	v_exp_f32_e32 v115, v28
	v_exp_f32_e32 v108, v13
	v_exp_f32_e32 v116, v29
	v_exp_f32_e32 v109, v14
	v_exp_f32_e32 v117, v30
	ds_read_b128 v[10:13], v35 offset:16384
	v_exp_f32_e32 v118, v15
	v_exp_f32_e32 v119, v31
	ds_read_b128 v[2:5], v35 offset:20480
	v_exp_f32_e32 v35, v16
	v_exp_f32_e32 v120, v32
	ds_read_b128 v[6:9], v48 offset:16384
	v_exp_f32_e32 v121, v17
	v_exp_f32_e32 v122, v33
	ds_read_b128 v[14:17], v48 offset:20480
	ds_read_b128 v[18:21], v49 offset:16384
	ds_read_b128 v[22:25], v49 offset:20480
	ds_read_b128 v[26:29], v50 offset:16384
	ds_read_b128 v[30:33], v50 offset:20480
	v_add_f32_e32 v36, 0, v52
	v_add_f32_e32 v36, v53, v36
	v_add_f32_e32 v36, v54, v36
	v_add_f32_e32 v36, v55, v36
	v_add_f32_e32 v36, v56, v36
	v_add_f32_e32 v36, v57, v36
	v_add_f32_e32 v36, v58, v36
	v_add_f32_e32 v36, v59, v36
	v_add_f32_e32 v36, v60, v36
	v_add_f32_e32 v36, v61, v36
	v_add_f32_e32 v36, v62, v36
	v_add_f32_e32 v36, v63, v36
	v_add_f32_e32 v36, v64, v36
	v_add_f32_e32 v36, v65, v36
	v_add_f32_e32 v36, v101, v36
	v_add_f32_e32 v36, v102, v36
	v_add_f32_e32 v36, v103, v36
	v_add_f32_e32 v36, v104, v36
	v_add_f32_e32 v36, v105, v36
	v_add_f32_e32 v36, v114, v36
	v_add_f32_e32 v36, v107, v36
	v_add_f32_e32 v36, v115, v36
	v_add_f32_e32 v36, v108, v36
	v_add_f32_e32 v36, v116, v36
	v_add_f32_e32 v36, v109, v36
	v_add_f32_e32 v36, v117, v36
	v_add_f32_e32 v36, v118, v36
	v_add_f32_e32 v36, v119, v36
	v_add_f32_e32 v36, v35, v36
	v_add_f32_e32 v36, v120, v36
	v_add_f32_e32 v36, v121, v36
	v_add_f32_e32 v36, v122, v36
	v_sub_u32_e32 v82, v34, v38
	v_pk_add_f32 v[198:199], v[36:37], 0 op_sel_hi:[1,0]
	v_add_u32_e32 v36, -1, v82
	v_add_u32_e32 v37, -3, v82
	v_add_u32_e32 v38, -2, v82
	v_add_u32_e32 v39, -5, v82
	v_add_u32_e32 v40, -4, v82
	v_add_u32_e32 v41, -7, v82
	v_add_u32_e32 v42, -6, v82
	v_subrev_u32_e32 v43, 17, v82
	v_add_u32_e32 v44, -16, v82
	v_subrev_u32_e32 v45, 19, v82
	v_subrev_u32_e32 v46, 18, v82
	v_subrev_u32_e32 v47, 21, v82
	v_subrev_u32_e32 v48, 20, v82
	v_subrev_u32_e32 v49, 23, v82
	v_subrev_u32_e32 v50, 22, v82
	v_cvt_f32_i32_e32 v50, v50
	v_cvt_f32_i32_e32 v51, v49
	v_cvt_f32_i32_e32 v48, v48
	v_cvt_f32_i32_e32 v49, v47
	v_cvt_f32_i32_e32 v46, v46
	v_cvt_f32_i32_e32 v47, v45
	v_cvt_f32_i32_e32 v44, v44
	v_cvt_f32_i32_e32 v45, v43
	v_cvt_f32_i32_e32 v42, v42
	v_cvt_f32_i32_e32 v43, v41
	v_cvt_f32_i32_e32 v40, v40
	v_cvt_f32_i32_e32 v41, v39
	v_cvt_f32_i32_e32 v39, v82
	v_cvt_f32_i32_e32 v66, v36
	v_cvt_f32_i32_e32 v67, v37
	v_cvt_f32_i32_e32 v38, v38
	v_and_b32_e32 v36, 0x7fffffff, v39
	v_and_b32_e32 v37, 0x7fffffff, v66
	v_and_b32_e32 v39, 0x7fffffff, v67
	v_and_b32_e32 v38, 0x7fffffff, v38
	v_and_b32_e32 v41, 0x7fffffff, v41
	v_and_b32_e32 v40, 0x7fffffff, v40
	v_and_b32_e32 v43, 0x7fffffff, v43
	v_and_b32_e32 v42, 0x7fffffff, v42
	v_and_b32_e32 v45, 0x7fffffff, v45
	v_and_b32_e32 v44, 0x7fffffff, v44
	v_and_b32_e32 v47, 0x7fffffff, v47
	v_and_b32_e32 v46, 0x7fffffff, v46
	v_and_b32_e32 v49, 0x7fffffff, v49
	v_and_b32_e32 v48, 0x7fffffff, v48
	v_and_b32_e32 v51, 0x7fffffff, v51
	v_and_b32_e32 v50, 0x7fffffff, v50
	v_pk_fma_f32 v[80:81], v[0:1], v[50:51], v[198:199] op_sel:[0,0,1] op_sel_hi:[0,1,1] neg_lo:[1,0,1] neg_hi:[1,0,1]
	v_pk_fma_f32 v[78:79], v[0:1], v[48:49], v[198:199] op_sel:[0,0,1] op_sel_hi:[0,1,1] neg_lo:[1,0,1] neg_hi:[1,0,1]
	v_pk_fma_f32 v[76:77], v[0:1], v[46:47], v[198:199] op_sel:[0,0,1] op_sel_hi:[0,1,1] neg_lo:[1,0,1] neg_hi:[1,0,1]
	v_pk_fma_f32 v[74:75], v[0:1], v[44:45], v[198:199] op_sel:[0,0,1] op_sel_hi:[0,1,1] neg_lo:[1,0,1] neg_hi:[1,0,1]
	v_pk_fma_f32 v[72:73], v[0:1], v[42:43], v[198:199] op_sel:[0,0,1] op_sel_hi:[0,1,1] neg_lo:[1,0,1] neg_hi:[1,0,1]
	v_pk_fma_f32 v[70:71], v[0:1], v[40:41], v[198:199] op_sel:[0,0,1] op_sel_hi:[0,1,1] neg_lo:[1,0,1] neg_hi:[1,0,1]
	v_pk_fma_f32 v[68:69], v[0:1], v[38:39], v[198:199] op_sel:[0,0,1] op_sel_hi:[0,1,1] neg_lo:[1,0,1] neg_hi:[1,0,1]
	v_pk_fma_f32 v[66:67], v[0:1], v[36:37], v[198:199] op_sel:[0,0,1] op_sel_hi:[0,1,1] neg_lo:[1,0,1] neg_hi:[1,0,1]
	v_subrev_u32_e32 v36, 33, v82
	v_subrev_u32_e32 v37, 32, v82
	v_subrev_u32_e32 v38, 35, v82
	v_subrev_u32_e32 v39, 34, v82
	v_subrev_u32_e32 v40, 37, v82
	v_subrev_u32_e32 v41, 36, v82
	v_subrev_u32_e32 v42, 39, v82
	v_subrev_u32_e32 v43, 38, v82
	v_subrev_u32_e32 v44, 49, v82
	v_subrev_u32_e32 v45, 48, v82
	v_subrev_u32_e32 v46, 51, v82
	v_subrev_u32_e32 v47, 50, v82
	v_subrev_u32_e32 v48, 53, v82
	v_subrev_u32_e32 v49, 52, v82
	v_subrev_u32_e32 v50, 55, v82
	v_subrev_u32_e32 v51, 54, v82
	v_cvt_f32_i32_e32 v82, v51
	v_cvt_f32_i32_e32 v50, v50
	v_cvt_f32_i32_e32 v51, v49
	v_cvt_f32_i32_e32 v48, v48
	v_cvt_f32_i32_e32 v49, v47
	v_cvt_f32_i32_e32 v46, v46
	v_cvt_f32_i32_e32 v47, v45
	v_cvt_f32_i32_e32 v44, v44
	v_cvt_f32_i32_e32 v45, v43
	v_cvt_f32_i32_e32 v42, v42
	v_cvt_f32_i32_e32 v43, v41
	v_cvt_f32_i32_e32 v40, v40
	v_cvt_f32_i32_e32 v36, v36
	v_cvt_f32_i32_e32 v41, v37
	v_cvt_f32_i32_e32 v38, v38
	v_cvt_f32_i32_e32 v83, v39
	v_and_b32_e32 v37, 0x7fffffff, v36
	v_and_b32_e32 v36, 0x7fffffff, v41
	v_and_b32_e32 v39, 0x7fffffff, v38
	v_and_b32_e32 v38, 0x7fffffff, v83
	v_and_b32_e32 v41, 0x7fffffff, v40
	v_and_b32_e32 v40, 0x7fffffff, v43
	v_and_b32_e32 v43, 0x7fffffff, v42
	v_and_b32_e32 v42, 0x7fffffff, v45
	v_and_b32_e32 v45, 0x7fffffff, v44
	v_and_b32_e32 v44, 0x7fffffff, v47
	v_and_b32_e32 v47, 0x7fffffff, v46
	v_and_b32_e32 v46, 0x7fffffff, v49
	v_and_b32_e32 v49, 0x7fffffff, v48
	v_and_b32_e32 v48, 0x7fffffff, v51
	v_and_b32_e32 v51, 0x7fffffff, v50
	v_and_b32_e32 v50, 0x7fffffff, v82
	v_pk_fma_f32 v[96:97], v[0:1], v[50:51], v[198:199] op_sel:[0,0,1] op_sel_hi:[0,1,1] neg_lo:[1,0,1] neg_hi:[1,0,1]
	v_pk_fma_f32 v[94:95], v[0:1], v[48:49], v[198:199] op_sel:[0,0,1] op_sel_hi:[0,1,1] neg_lo:[1,0,1] neg_hi:[1,0,1]
	v_pk_fma_f32 v[92:93], v[0:1], v[46:47], v[198:199] op_sel:[0,0,1] op_sel_hi:[0,1,1] neg_lo:[1,0,1] neg_hi:[1,0,1]
	v_pk_fma_f32 v[90:91], v[0:1], v[44:45], v[198:199] op_sel:[0,0,1] op_sel_hi:[0,1,1] neg_lo:[1,0,1] neg_hi:[1,0,1]
	v_pk_fma_f32 v[88:89], v[0:1], v[42:43], v[198:199] op_sel:[0,0,1] op_sel_hi:[0,1,1] neg_lo:[1,0,1] neg_hi:[1,0,1]
	v_pk_fma_f32 v[86:87], v[0:1], v[40:41], v[198:199] op_sel:[0,0,1] op_sel_hi:[0,1,1] neg_lo:[1,0,1] neg_hi:[1,0,1]
	v_pk_fma_f32 v[84:85], v[0:1], v[38:39], v[198:199] op_sel:[0,0,1] op_sel_hi:[0,1,1] neg_lo:[1,0,1] neg_hi:[1,0,1]
	v_pk_fma_f32 v[82:83], v[0:1], v[36:37], v[198:199] op_sel:[0,0,1] op_sel_hi:[0,1,1] neg_lo:[1,0,1] neg_hi:[1,0,1]
	s_waitcnt lgkmcnt(0)
	v_mfma_f32_32x32x16_bf16 v[66:81], v[10:13], v[130:133], v[66:81]
	v_cvt_pk_bf16_f32 v98, v52, v54
	v_cvt_pk_bf16_f32 v99, v56, v58
	v_cvt_pk_bf16_f32 v100, v60, v62
	v_cvt_pk_bf16_f32 v101, v64, v101
	v_cvt_pk_bf16_f32 v110, v53, v55
	v_cvt_pk_bf16_f32 v111, v57, v59
	v_cvt_pk_bf16_f32 v112, v61, v63
	v_mfma_f32_32x32x16_bf16 v[82:97], v[2:5], v[130:133], v[82:97]
	v_cvt_pk_bf16_f32 v113, v65, v102
	v_cvt_pk_bf16_f32 v106, v103, v105
	v_cvt_pk_bf16_f32 v107, v107, v108
	v_cvt_pk_bf16_f32 v108, v109, v118
	v_cvt_pk_bf16_f32 v109, v35, v121
	v_cvt_pk_bf16_f32 v114, v104, v114
	v_cvt_pk_bf16_f32 v115, v115, v116
	v_mfma_f32_32x32x16_bf16 v[66:81], v[6:9], v[134:137], v[66:81]
	v_cvt_pk_bf16_f32 v116, v117, v119
	s_cmp_lt_i32 s48, 2
	v_cvt_pk_bf16_f32 v117, v120, v122
	v_mfma_f32_32x32x16_bf16 v[82:97], v[14:17], v[134:137], v[82:97]
	v_mfma_f32_32x32x16_bf16 v[66:81], v[18:21], v[138:141], v[66:81]
	v_mfma_f32_32x32x16_bf16 v[82:97], v[22:25], v[138:141], v[82:97]
	v_mfma_f32_32x32x16_bf16 v[66:81], v[26:29], v[142:145], v[66:81]
	v_mfma_f32_32x32x16_bf16 v[82:97], v[30:33], v[142:145], v[82:97]
	s_cbranch_scc1 .LBB0_472
	v_sub_u32_e32 v0, v148, v34
	v_cvt_f32_i32_e32 v155, v0
	v_mov_b32_e32 v16, v153
	v_mov_b32_e32 v17, v153
	v_mov_b32_e32 v2, v153
	v_mov_b32_e32 v3, v153
	v_mov_b32_e32 v4, v153
	v_mov_b32_e32 v5, v153
	v_mov_b32_e32 v6, v153
	v_mov_b32_e32 v7, v153
	v_mov_b32_e32 v8, v153
	v_mov_b32_e32 v9, v153
	v_mov_b32_e32 v10, v153
	v_mov_b32_e32 v11, v153
	v_mov_b32_e32 v12, v153
	v_mov_b32_e32 v13, v153
	v_mov_b32_e32 v14, v153
	v_mov_b32_e32 v15, v153
	v_mov_b64_e32 v[32:33], v[16:17]
	v_mov_b64_e32 v[48:49], v[16:17]
	v_mov_b64_e32 v[64:65], v[16:17]
	s_mov_b64 s[2:3], 0
	v_mov_b32_e32 v0, 1.0
	s_mov_b32 s62, 2
	s_mov_b32 s34, 5
	v_mov_b64_e32 v[30:31], v[14:15]
	v_mov_b64_e32 v[28:29], v[12:13]
	v_mov_b64_e32 v[26:27], v[10:11]
	v_mov_b64_e32 v[24:25], v[8:9]
	v_mov_b64_e32 v[22:23], v[6:7]
	v_mov_b64_e32 v[20:21], v[4:5]
	v_mov_b64_e32 v[18:19], v[2:3]
	v_mov_b64_e32 v[46:47], v[14:15]
	v_mov_b64_e32 v[44:45], v[12:13]
	v_mov_b64_e32 v[42:43], v[10:11]
	v_mov_b64_e32 v[40:41], v[8:9]
	v_mov_b64_e32 v[38:39], v[6:7]
	v_mov_b64_e32 v[36:37], v[4:5]
	v_mov_b64_e32 v[34:35], v[2:3]
	v_mov_b64_e32 v[62:63], v[14:15]
	v_mov_b64_e32 v[60:61], v[12:13]
	v_mov_b64_e32 v[58:59], v[10:11]
	v_mov_b64_e32 v[56:57], v[8:9]
	v_mov_b64_e32 v[54:55], v[6:7]
	v_mov_b64_e32 v[52:53], v[4:5]
	v_mov_b64_e32 v[50:51], v[2:3]
	s_mov_b32 s81, 0
	s_mov_b32 s83, 0
	s_mov_b32 s85, 0
	s_add_i32 s61, s34, -2
	s_cmp_gt_i32 s61, s48
	s_mov_b64 s[4:5], -1
	s_cbranch_scc0 .LBB0_468

.Lattn_A_fast:
	s_lshl_b32 s80, s10, 14
	v_add_u32_e32 v179, s80, v219
	v_add_u32_e32 v126, v179, v149
	ds_read_b128 v[102:105], v126 offset:49152
	ds_read_b128 v[118:121], v126 offset:53248
	ds_read_b128 v[122:125], v126 offset:57344
	ds_read_b128 v[228:231], v126 offset:61440
	s_add_i32 s63, s60, 0x80
	s_lshl_b32 s79, s62, 14
	s_cmp_ge_i32 s61, s48
	s_cselect_b32 s4, 0, 1
	s_waitcnt lgkmcnt(2)
	v_mfma_f32_32x32x16_bf16 v[50:65], v[102:105], v[98:101], v[50:65]
	v_exp_f32_e32 v66, v66
	v_exp_f32_e32 v249, v82
	v_add_u32_e32 v181, v179, v208
	ds_read_b128 v[102:105], v181 offset:49152
	v_mfma_f32_32x32x16_bf16 v[34:49], v[118:121], v[98:101], v[34:49]
	v_add_f32_e32 v254, 0, v66
	v_add_f32_e32 v255, 0, v249
	v_exp_f32_e32 v67, v67
	v_exp_f32_e32 v250, v83
	ds_read_b128 v[232:235], v181 offset:53248
	s_waitcnt lgkmcnt(2)
	v_mfma_f32_32x32x16_bf16 v[18:33], v[122:125], v[98:101], v[18:33]
	v_add_f32_e32 v254, v67, v254
	v_add_f32_e32 v255, v250, v255
	v_exp_f32_e32 v68, v68
	v_exp_f32_e32 v195, v84
	ds_read_b128 v[126:129], v181 offset:57344
	v_mfma_f32_32x32x16_bf16 v[2:17], v[228:231], v[98:101], v[2:17]
	v_add_f32_e32 v254, v68, v254
	v_add_f32_e32 v255, v195, v255
	v_exp_f32_e32 v69, v69
	v_exp_f32_e32 v251, v85
	ds_read_b128 v[118:121], v181 offset:61440
	s_waitcnt lgkmcnt(2)
	v_mfma_f32_32x32x16_bf16 v[50:65], v[102:105], v[106:109], v[50:65]
	v_add_f32_e32 v254, v69, v254
	v_add_f32_e32 v255, v251, v255
	v_exp_f32_e32 v70, v70
	v_exp_f32_e32 v252, v86
	v_add_u32_e32 v181, v179, v209
	ds_read_b128 v[122:125], v181 offset:49152
	v_mfma_f32_32x32x16_bf16 v[34:49], v[232:235], v[106:109], v[34:49]
	s_cbranch_scc1 .LBB0_458
	s_add_i32 s82, s60, 0x100
	s_cmp_le_i32 s61, s39
	s_cselect_b32 s82, s63, s82
	s_lshl_b32 s82, s82, 12
	s_add_i32 s78, s79, 0xffffc000
	s_cmp_lg_u32 s62, 0
	s_cselect_b32 s78, s78, 0x8000
	v_lshl_add_u64 v[98:99], v[202:203], 0, s[82:83]
	s_add_i32 s78, s7, s78
	s_mov_b32 m0, s78
	v_lshl_add_u64 v[100:101], v[98:99], 0, s[30:31]
	global_load_lds_dwordx4 v[100:101], off
	s_add_i32 m0, s78, 0x2000
	v_lshl_add_u64 v[98:99], v[98:99], 0, s[36:37]
	global_load_lds_dwordx4 v[98:99], off
.LBB0_458:
	s_add_i32 s78, s34, -4
	s_cmp_gt_i32 s78, s39
	s_cselect_b64 vcc, -1, 0
	s_cselect_b32 s82, s63, s60
	v_cndmask_b32_e64 v200, v201, -v201, vcc
	s_lshl_b32 s84, s82, 1
	s_addk_i32 s80, 0xc000
	s_cmp_lg_u32 s10, 0
	s_cselect_b32 s80, s80, 0x8000
	s_add_i32 s80, s14, s80
	v_lshl_add_u64 v[98:99], v[204:205], 0, s[84:85]
	s_add_i32 m0, s80, 0xc000
	v_lshl_add_u64 v[100:101], v[206:207], 0, s[84:85]
	global_load_lds_dwordx4 v[98:99], off
	s_add_i32 m0, s80, 0xc400
	v_cvt_f32_i32_e32 v98, s82
	global_load_lds_dwordx4 v[100:101], off
	v_add_u32_e32 v183, s79, v218
	v_add_f32_e32 v98, v155, v98
	v_fma_f32 v224, v200, v98, -v199
	v_fma_f32 v98, 0, v200, v224
	v_add_f32_e32 v99, v200, v224
	v_fma_f32 v100, v200, s64, v224
	v_fma_f32 v101, v200, s65, v224
	v_fma_f32 v102, v200, s66, v224
	v_fma_f32 v103, v200, s67, v224
	v_mul_f32_e32 v240, 0x42000000, v200
	ds_read_b128 v[228:231], v181 offset:53248
	s_waitcnt lgkmcnt(2)
	v_mfma_f32_32x32x16_bf16 v[18:33], v[126:129], v[106:109], v[18:33]
	v_add_f32_e32 v254, v70, v254
	v_add_f32_e32 v255, v252, v255
	v_exp_f32_e32 v71, v71
	v_fma_f32 v104, v200, s68, v224
	v_fma_f32 v105, v200, s69, v224
	ds_read_b128 v[126:129], v181 offset:57344
	v_mfma_f32_32x32x16_bf16 v[2:17], v[118:121], v[106:109], v[2:17]
	s_setprio 0
	v_add_f32_e32 v254, v71, v254
	v_exp_f32_e32 v253, v87
	v_exp_f32_e32 v82, v72
	ds_read_b128 v[118:121], v181 offset:61440
	s_waitcnt lgkmcnt(2)
	v_mfma_f32_32x32x16_bf16 v[50:65], v[122:125], v[110:113], v[50:65]
	v_add_f32_e32 v255, v253, v255
	v_add_f32_e32 v254, v82, v254
	v_exp_f32_e32 v72, v88
	v_fma_f32 v106, v200, s70, v224
	v_fma_f32 v107, v200, s71, v224
	v_add_u32_e32 v179, v179, v226
	ds_read_b128 v[122:125], v179 offset:49152
	v_mfma_f32_32x32x16_bf16 v[34:49], v[228:231], v[110:113], v[34:49]
	v_add_f32_e32 v255, v72, v255
	v_exp_f32_e32 v83, v73
	v_exp_f32_e32 v73, v89
	ds_read_b128 v[228:231], v179 offset:53248
	s_waitcnt lgkmcnt(2)
	v_mfma_f32_32x32x16_bf16 v[18:33], v[126:129], v[110:113], v[18:33]
	v_add_f32_e32 v254, v83, v254
	v_add_f32_e32 v255, v73, v255
	v_exp_f32_e32 v74, v74
	v_fma_f32 v108, v200, s72, v224
	v_fma_f32 v109, v200, s73, v224
	ds_read_b128 v[126:129], v179 offset:57344
	v_mfma_f32_32x32x16_bf16 v[2:17], v[118:121], v[110:113], v[2:17]
	v_add_f32_e32 v254, v74, v254
	v_exp_f32_e32 v90, v90
	v_exp_f32_e32 v75, v75
	ds_read_b128 v[118:121], v179 offset:61440
	s_waitcnt lgkmcnt(2)
	v_mfma_f32_32x32x16_bf16 v[50:65], v[122:125], v[114:117], v[50:65]
	v_add_f32_e32 v255, v90, v255
	v_add_f32_e32 v254, v75, v254
	v_exp_f32_e32 v91, v91
	v_fma_f32 v110, v200, s74, v224
	v_fma_f32 v111, v200, s75, v224
	v_add_u32_e32 v112, v183, v149
	ds_read_b128 v[232:235], v112
	v_mfma_f32_32x32x16_bf16 v[34:49], v[228:231], v[114:117], v[34:49]
	v_add_f32_e32 v255, v91, v255
	v_exp_f32_e32 v76, v76
	v_exp_f32_e32 v92, v92
	ds_read_b128 v[228:231], v112 offset:4096
	s_waitcnt lgkmcnt(2)
	v_mfma_f32_32x32x16_bf16 v[18:33], v[126:129], v[114:117], v[18:33]
	v_add_f32_e32 v254, v76, v254
	v_add_f32_e32 v255, v92, v255
	v_exp_f32_e32 v77, v77
	v_fma_f32 v112, v200, s76, v224
	v_fma_f32 v113, v200, s77, v224
	v_add_u32_e32 v179, v183, v208
	ds_read_b128 v[236:239], v179
	v_mfma_f32_32x32x16_bf16 v[2:17], v[118:121], v[114:117], v[2:17]
	v_add_f32_e64 v114, v240, v98
	v_add_f32_e64 v115, v240, v99
	v_add_f32_e64 v128, v240, v112
	v_add_f32_e64 v129, v240, v113
	v_add_f32_e64 v126, v240, v110
	v_add_f32_e64 v127, v240, v111
	v_add_f32_e32 v124, v240, v108
	v_add_f32_e32 v125, v240, v109
	v_add_f32_e32 v122, v240, v106
	v_add_f32_e32 v123, v240, v107
	v_add_f32_e32 v120, v240, v104
	v_add_f32_e32 v121, v240, v105
	v_add_f32_e32 v118, v240, v102
	v_add_f32_e32 v119, v240, v103
	v_add_f32_e32 v116, v240, v100
	v_add_f32_e32 v117, v240, v101
	ds_read_b128 v[240:243], v179 offset:4096
	s_waitcnt lgkmcnt(2)
	v_mfma_f32_32x32x16_bf16 v[98:113], v[232:235], v[130:133], v[98:113]
	v_add_f32_e32 v254, v77, v254
	v_exp_f32_e32 v93, v93
	v_exp_f32_e32 v78, v78
	v_add_u32_e32 v179, v183, v209
	ds_read_b128 v[232:235], v179
	v_mfma_f32_32x32x16_bf16 v[114:129], v[228:231], v[130:133], v[114:129]
	v_add_f32_e32 v255, v93, v255
	v_add_f32_e32 v254, v78, v254
	v_exp_f32_e32 v94, v94
	v_exp_f32_e32 v79, v79
	ds_read_b128 v[228:231], v179 offset:4096
	s_waitcnt lgkmcnt(2)
	v_mfma_f32_32x32x16_bf16 v[98:113], v[236:239], v[134:137], v[98:113]
	v_add_f32_e32 v255, v94, v255
	v_add_f32_e32 v254, v79, v254
	v_exp_f32_e32 v95, v95
	v_exp_f32_e32 v80, v80
	v_add_u32_e32 v179, v183, v226
	ds_read_b128 v[236:239], v179
	v_mfma_f32_32x32x16_bf16 v[114:129], v[240:243], v[134:137], v[114:129]
	v_add_f32_e32 v255, v95, v255
	v_add_f32_e32 v254, v80, v254
	v_exp_f32_e32 v96, v96
	v_exp_f32_e32 v81, v81
	ds_read_b128 v[240:243], v179 offset:4096
	s_waitcnt lgkmcnt(2)
	v_mfma_f32_32x32x16_bf16 v[98:113], v[232:235], v[138:141], v[98:113]
	v_add_f32_e32 v255, v96, v255
	v_add_f32_e32 v254, v81, v254
	v_exp_f32_e32 v97, v97
	v_mfma_f32_32x32x16_bf16 v[114:129], v[228:231], v[138:141], v[114:129]
	v_add_f32_e32 v255, v97, v255
	v_add_f32_e32 v254, v255, v254
	s_waitcnt lgkmcnt(0)
	v_mfma_f32_32x32x16_bf16 v[98:113], v[236:239], v[142:145], v[98:113]
	v_mfma_f32_32x32x16_bf16 v[114:129], v[240:243], v[142:145], v[114:129]
	s_cmp_lg_u32 s4, 0
	s_cbranch_scc0 .LBB0_471
	s_waitcnt vmcnt(4) lgkmcnt(0)
	s_barrier
	s_cmp_eq_u32 s100, 0
	s_cbranch_scc1 .Lattn_fair_a
	s_setprio 1

.LBB0_464:
	s_add_i32 s4, s62, 1
	s_cmp_lg_u32 s62, 2
	s_cselect_b32 s4, s4, 0
	s_add_i32 s5, s10, 1
	s_cmp_lg_u32 s10, 2
	s_cselect_b32 s5, s5, 0
	s_lshl_b32 s62, s5, 14
	v_add_u32_e32 v198, s62, v219
	v_cvt_pk_bf16_f32 v66, v66, v67
	v_cvt_pk_bf16_f32 v67, v68, v69
	v_cvt_pk_bf16_f32 v68, v70, v71
	v_add_u32_e32 v70, v198, v149
	v_cvt_pk_bf16_f32 v69, v82, v83
	v_cvt_pk_bf16_f32 v74, v74, v75
	v_cvt_pk_bf16_f32 v75, v76, v77
	v_cvt_pk_bf16_f32 v76, v78, v79
	v_cvt_pk_bf16_f32 v77, v80, v81
	ds_read_b128 v[78:81], v70 offset:49152
	ds_read_b128 v[82:85], v70 offset:53248
	ds_read_b128 v[86:89], v70 offset:57344
	ds_read_b128 v[228:231], v70 offset:61440
	s_lshl_b32 s10, s4, 14
	s_cmp_gt_i32 s34, s48
	s_waitcnt lgkmcnt(2)
	v_mfma_f32_32x32x16_bf16 v[50:65], v[78:81], v[66:69], v[50:65]
	v_add_u32_e32 v70, v198, v208
	ds_read_b128 v[78:81], v70 offset:49152
	v_mfma_f32_32x32x16_bf16 v[34:49], v[82:85], v[66:69], v[34:49]
	ds_read_b128 v[232:235], v70 offset:53248
	s_waitcnt lgkmcnt(2)
	v_mfma_f32_32x32x16_bf16 v[18:33], v[86:89], v[66:69], v[18:33]
	ds_read_b128 v[86:89], v70 offset:57344
	v_mfma_f32_32x32x16_bf16 v[2:17], v[228:231], v[66:69], v[2:17]
	ds_read_b128 v[82:85], v70 offset:61440
	s_waitcnt lgkmcnt(2)
	v_mfma_f32_32x32x16_bf16 v[50:65], v[78:81], v[74:77], v[50:65]
	v_add_u32_e32 v227, v198, v209
	ds_read_b128 v[78:81], v227 offset:49152
	v_mfma_f32_32x32x16_bf16 v[34:49], v[232:235], v[74:77], v[34:49]
	s_cbranch_scc1 .LBB0_466
	s_cmp_lt_i32 s61, s39
	s_movk_i32 s79, 0xc0
	s_cselect_b32 s79, s79, 0x140
	s_add_i32 s80, s60, s79
	s_lshl_b32 s80, s80, 12
	s_add_i32 s60, s10, 0xffffc000
	s_cmp_lg_u32 s4, 0
	s_cselect_b32 s60, s60, 0x8000
	v_lshl_add_u64 v[66:67], v[202:203], 0, s[80:81]
	s_add_i32 s60, s7, s60
	s_mov_b32 m0, s60
	v_lshl_add_u64 v[68:69], v[66:67], 0, s[30:31]
	global_load_lds_dwordx4 v[68:69], off
	s_add_i32 m0, s60, 0x2000
	v_lshl_add_u64 v[66:67], v[66:67], 0, s[36:37]
	global_load_lds_dwordx4 v[66:67], off
.LBB0_466:
	s_cmp_lt_i32 s78, s39
	s_cselect_b64 vcc, -1, 0
	s_cselect_b32 s60, s78, s61
	v_cndmask_b32_e64 v228, -v201, v201, vcc
	s_add_i32 s60, s60, s33
	s_lshl_b32 s78, s60, 6
	s_lshl_b32 s80, s78, 1
	s_addk_i32 s62, 0xc000
	s_cmp_lg_u32 s5, 0
	s_cselect_b32 s60, s62, 0x8000
	s_add_i32 s60, s14, s60
	v_lshl_add_u64 v[66:67], v[204:205], 0, s[80:81]
	s_add_i32 m0, s60, 0xc000
	v_lshl_add_u64 v[68:69], v[206:207], 0, s[80:81]
	global_load_lds_dwordx4 v[66:67], off
	s_add_i32 m0, s60, 0xc400
	v_cvt_f32_i32_e32 v66, s78
	global_load_lds_dwordx4 v[68:69], off
	v_exp_f32_e32 v231, v98
	v_add_f32_e32 v66, v155, v66
	v_fma_f32 v230, v228, v66, -v199
	v_add_u32_e32 v229, s10, v218
	v_exp_f32_e32 v233, v114
	v_fma_f32 v66, 0, v228, v230
	v_exp_f32_e32 v234, v99
	v_exp_f32_e32 v235, v115
	v_add_f32_e32 v67, v228, v230
	v_exp_f32_e32 v236, v100
	v_exp_f32_e32 v237, v116
	v_exp_f32_e32 v238, v101
	v_exp_f32_e32 v239, v117
	v_fma_f32 v68, v228, s64, v230
	v_fma_f32 v69, v228, s65, v230
	v_fma_f32 v70, v228, s66, v230
	v_fma_f32 v71, v228, s67, v230
	v_cvt_pk_bf16_f32 v98, v249, v250
	v_cvt_pk_bf16_f32 v99, v195, v251
	v_cvt_pk_bf16_f32 v100, v252, v253
	v_cvt_pk_bf16_f32 v101, v72, v73
	v_cvt_pk_bf16_f32 v114, v90, v91
	v_cvt_pk_bf16_f32 v115, v92, v93
	v_cvt_pk_bf16_f32 v116, v94, v95
	v_cvt_pk_bf16_f32 v117, v96, v97
	v_mul_f32_e32 v232, 0x42000000, v228
	v_exp_f32_e32 v240, v102
	v_exp_f32_e32 v241, v118
	v_exp_f32_e32 v242, v103
	v_exp_f32_e32 v243, v119
	ds_read_b128 v[90:93], v227 offset:53248
	s_waitcnt lgkmcnt(2)
	v_mfma_f32_32x32x16_bf16 v[18:33], v[86:89], v[74:77], v[18:33]
	v_add_f32_e32 v254, 0, v231
	v_add_f32_e32 v255, 0, v233
	v_fma_f32 v72, v228, s68, v230
	v_fma_f32 v73, v228, s69, v230
	v_exp_f32_e32 v181, v104
	v_exp_f32_e32 v183, v120
	ds_read_b128 v[86:89], v227 offset:57344
	v_mfma_f32_32x32x16_bf16 v[2:17], v[82:85], v[74:77], v[2:17]
	s_setprio 0
	v_add_f32_e32 v254, v234, v254
	v_add_f32_e32 v255, v235, v255
	v_exp_f32_e32 v195, v105
	v_exp_f32_e32 v200, v121
	ds_read_b128 v[82:85], v227 offset:61440
	s_waitcnt lgkmcnt(2)
	v_mfma_f32_32x32x16_bf16 v[50:65], v[78:81], v[98:101], v[50:65]
	v_add_f32_e32 v254, v236, v254
	v_add_f32_e32 v255, v237, v255
	v_fma_f32 v74, v228, s70, v230
	v_fma_f32 v75, v228, s71, v230
	v_exp_f32_e32 v224, v106
	v_exp_f32_e32 v122, v122
	v_add_u32_e32 v78, v198, v226
	ds_read_b128 v[94:97], v78 offset:49152
	v_mfma_f32_32x32x16_bf16 v[34:49], v[90:93], v[98:101], v[34:49]
	v_add_f32_e32 v254, v238, v254
	v_add_f32_e32 v255, v239, v255
	v_exp_f32_e32 v225, v107
	v_exp_f32_e32 v123, v123
	ds_read_b128 v[90:93], v78 offset:53248
	s_waitcnt lgkmcnt(2)
	v_mfma_f32_32x32x16_bf16 v[18:33], v[86:89], v[98:101], v[18:33]
	v_add_f32_e32 v254, v240, v254
	v_add_f32_e32 v255, v241, v255
	v_fma_f32 v76, v228, s72, v230
	v_fma_f32 v77, v228, s73, v230
	v_exp_f32_e32 v227, v108
	v_exp_f32_e32 v124, v124
	ds_read_b128 v[86:89], v78 offset:57344
	v_mfma_f32_32x32x16_bf16 v[2:17], v[82:85], v[98:101], v[2:17]
	v_add_f32_e32 v254, v242, v254
	v_add_f32_e32 v255, v243, v255
	v_exp_f32_e32 v244, v109
	v_exp_f32_e32 v125, v125
	ds_read_b128 v[98:101], v78 offset:61440
	s_waitcnt lgkmcnt(2)
	v_mfma_f32_32x32x16_bf16 v[50:65], v[94:97], v[114:117], v[50:65]
	v_add_f32_e32 v254, v181, v254
	v_add_f32_e32 v255, v183, v255
	v_fma_f32 v78, v228, s74, v230
	v_fma_f32 v79, v228, s75, v230
	v_exp_f32_e32 v245, v110
	v_exp_f32_e32 v126, v126
	v_add_u32_e32 v80, v229, v149
	ds_read_b128 v[102:105], v80
	v_mfma_f32_32x32x16_bf16 v[34:49], v[90:93], v[114:117], v[34:49]
	v_add_f32_e32 v254, v195, v254
	v_add_f32_e32 v255, v200, v255
	v_exp_f32_e32 v246, v111
	v_exp_f32_e32 v127, v127
	ds_read_b128 v[106:109], v80 offset:4096
	s_waitcnt lgkmcnt(2)
	v_mfma_f32_32x32x16_bf16 v[18:33], v[86:89], v[114:117], v[18:33]
	v_add_f32_e32 v254, v224, v254
	v_add_f32_e32 v255, v122, v255
	v_fma_f32 v80, v228, s76, v230
	v_fma_f32 v81, v228, s77, v230
	v_exp_f32_e32 v247, v112
	v_exp_f32_e32 v128, v128
	v_add_u32_e32 v110, v229, v208
	ds_read_b128 v[118:121], v110
	v_mfma_f32_32x32x16_bf16 v[2:17], v[98:101], v[114:117], v[2:17]
	v_add_f32_e32 v254, v225, v254
	v_add_f32_e32 v255, v123, v255
	v_add_f32_e64 v82, v232, v66
	v_add_f32_e64 v83, v232, v67
	v_add_f32_e64 v96, v232, v80
	v_add_f32_e64 v97, v232, v81
	v_add_f32_e64 v94, v232, v78
	v_add_f32_e64 v95, v232, v79
	v_add_f32_e32 v92, v232, v76
	v_add_f32_e32 v93, v232, v77
	v_add_f32_e32 v90, v232, v74
	v_add_f32_e32 v91, v232, v75
	v_add_f32_e32 v88, v232, v72
	v_add_f32_e32 v89, v232, v73
	v_add_f32_e32 v86, v232, v70
	v_add_f32_e32 v87, v232, v71
	v_add_f32_e32 v84, v232, v68
	v_add_f32_e32 v85, v232, v69
	v_exp_f32_e32 v228, v113
	v_exp_f32_e32 v129, v129
	ds_read_b128 v[98:101], v110 offset:4096
	s_waitcnt lgkmcnt(2)
	v_mfma_f32_32x32x16_bf16 v[66:81], v[102:105], v[130:133], v[66:81]
	v_add_f32_e32 v254, v227, v254
	v_add_f32_e32 v255, v124, v255
	v_add_f32_e32 v254, v244, v254
	v_add_u32_e32 v110, v229, v209
	ds_read_b128 v[102:105], v110
	v_mfma_f32_32x32x16_bf16 v[82:97], v[106:109], v[130:133], v[82:97]
	v_add_f32_e32 v255, v125, v255
	v_add_f32_e32 v254, v245, v254
	v_add_f32_e32 v255, v126, v255
	ds_read_b128 v[106:109], v110 offset:4096
	s_waitcnt lgkmcnt(2)
	v_mfma_f32_32x32x16_bf16 v[66:81], v[118:121], v[134:137], v[66:81]
	v_add_f32_e32 v254, v246, v254
	v_add_f32_e32 v255, v127, v255
	v_add_f32_e32 v254, v247, v254
	v_add_u32_e32 v114, v229, v226
	ds_read_b128 v[110:113], v114
	v_mfma_f32_32x32x16_bf16 v[82:97], v[98:101], v[134:137], v[82:97]
	v_add_f32_e32 v255, v128, v255
	v_add_f32_e32 v254, v228, v254
	v_add_f32_e32 v255, v129, v255
	v_add_f32_e32 v254, v255, v254
	ds_read_b128 v[98:101], v114 offset:4096
	s_waitcnt lgkmcnt(2)
	v_mfma_f32_32x32x16_bf16 v[66:81], v[102:105], v[138:141], v[66:81]
	v_cvt_pk_bf16_f32 v114, v122, v123
	v_cvt_pk_bf16_f32 v115, v124, v125
	v_cvt_pk_bf16_f32 v116, v126, v127
	v_cvt_pk_bf16_f32 v117, v128, v129
	v_mfma_f32_32x32x16_bf16 v[82:97], v[106:109], v[138:141], v[82:97]
	v_cvt_pk_bf16_f32 v106, v224, v225
	v_cvt_pk_bf16_f32 v107, v227, v244
	v_cvt_pk_bf16_f32 v108, v245, v246
	v_cvt_pk_bf16_f32 v109, v247, v228
	s_waitcnt lgkmcnt(0)
	v_mfma_f32_32x32x16_bf16 v[66:81], v[110:113], v[142:145], v[66:81]
	v_cvt_pk_bf16_f32 v110, v233, v235
	v_cvt_pk_bf16_f32 v111, v237, v239
	v_cvt_pk_bf16_f32 v112, v241, v243
	v_cvt_pk_bf16_f32 v113, v183, v200
	v_mfma_f32_32x32x16_bf16 v[82:97], v[98:101], v[142:145], v[82:97]
	s_add_i32 s10, s4, 1
	s_cmp_lg_u32 s4, 2
	s_cselect_b32 s62, s10, 0
	s_add_i32 s4, s5, 1
	s_cmp_lg_u32 s5, 2
	s_cselect_b32 s10, s4, 0
	s_add_i32 s34, s34, 2
	v_add_f32_e32 v198, v179, v254
	v_cvt_pk_bf16_f32 v98, v231, v234
	v_cvt_pk_bf16_f32 v99, v236, v238
	v_cvt_pk_bf16_f32 v100, v240, v242
	v_cvt_pk_bf16_f32 v101, v181, v195
	s_cmp_ge_i32 s61, s48
	s_cbranch_scc1 .LBB0_473
	s_mov_b32 s60, s63
	s_add_i32 s61, s34, -2
	s_cmp_gt_i32 s61, s48
	s_cbranch_scc1 .LBB0_469
